# LRU item loops wait only for the LDS-DMA prefetch (vmcnt(4)), LRU weight staging unrolled, P10c no store wait at loop top, V pass waits fixed so next visit's gathers overlap the MFMAs
# speedup vs baseline: 1.0616x; 1.0210x over previous
; #define LAS __attribute__((address_space(3)))
; template <int PASS>
; __device__ __forceinline__ void lru_phase(Frame& F, const Params& p) {
;     ...
;     for (int i = F.tid; i < 4 * 64 * 8; i += NTHREADS) {
;         const int c = i & 7, j = (i >> 3) & 63, m = i >> 9, d = m >> 1, gt = m & 1;
;         const u32x4 w = *(const u32x4*)((const bf16*)(F.ws + WS_LW) + ((size_t)(((d * 16 + head) * 2 + gt) * 64 + j) * 64 + 8 * c));
;         *(LAS u32x4*)(lw + (m * 64 + j) * LRU_WROW + 8 * c) = w;
;     }
.LBB0_662:
	v_mov_b32_e32 v17, 0
	v_add_u32_e32 v24, 0, v4
	v_add_u32_e32 v25, 0, v1
	v_lshrrev_b32_e32 v16, 6, v24
	v_lshlrev_b32_e32 v20, 1, v25
	v_and_b32_e32 v21, 0x1fffff0, v16
	v_ashrrev_i32_e32 v23, 3, v24
	v_and_b32_e32 v16, 0x70, v20
	v_or_b32_e32 v20, s48, v21
	v_bfe_u32 v18, v24, 3, 6
	v_and_b32_e32 v22, 64, v23
	v_lshlrev_b32_e32 v20, 7, v20
	v_or3_b32 v20, v20, v22, v18
	v_ashrrev_i32_e32 v21, 31, v20
	v_lshlrev_b64 v[20:21], 7, v[20:21]
	v_lshl_add_u64 v[20:21], s[6:7], 0, v[20:21]
	v_lshl_add_u64 v[20:21], v[20:21], 0, v[16:17]
	global_load_dwordx4 v[32:35], v[20:21], off
	v_and_or_b32 v18, v23, s10, v18
	v_mul_lo_u32 v18, v18, s11
	v_add3_u32 v28, 0, v18, v16
	v_add_u32_e32 v24, 512, v4
	v_add_u32_e32 v25, 4096, v1
	v_lshrrev_b32_e32 v16, 6, v24
	v_lshlrev_b32_e32 v20, 1, v25
	v_and_b32_e32 v21, 0x1fffff0, v16
	v_ashrrev_i32_e32 v23, 3, v24
	v_and_b32_e32 v16, 0x70, v20
	v_or_b32_e32 v20, s48, v21
	v_bfe_u32 v18, v24, 3, 6
	v_and_b32_e32 v22, 64, v23
	v_lshlrev_b32_e32 v20, 7, v20
	v_or3_b32 v20, v20, v22, v18
	v_ashrrev_i32_e32 v21, 31, v20
	v_lshlrev_b64 v[20:21], 7, v[20:21]
	v_lshl_add_u64 v[20:21], s[6:7], 0, v[20:21]
	v_lshl_add_u64 v[20:21], v[20:21], 0, v[16:17]
	global_load_dwordx4 v[36:39], v[20:21], off
	v_and_or_b32 v18, v23, s10, v18
	v_mul_lo_u32 v18, v18, s11
	v_add3_u32 v29, 0, v18, v16
	v_add_u32_e32 v24, 1024, v4
	v_add_u32_e32 v25, 8192, v1
	v_lshrrev_b32_e32 v16, 6, v24
	v_lshlrev_b32_e32 v20, 1, v25
	v_and_b32_e32 v21, 0x1fffff0, v16
	v_ashrrev_i32_e32 v23, 3, v24
	v_and_b32_e32 v16, 0x70, v20
	v_or_b32_e32 v20, s48, v21
	v_bfe_u32 v18, v24, 3, 6
	v_and_b32_e32 v22, 64, v23
	v_lshlrev_b32_e32 v20, 7, v20
	v_or3_b32 v20, v20, v22, v18
	v_ashrrev_i32_e32 v21, 31, v20
	v_lshlrev_b64 v[20:21], 7, v[20:21]
	v_lshl_add_u64 v[20:21], s[6:7], 0, v[20:21]
	v_lshl_add_u64 v[20:21], v[20:21], 0, v[16:17]
	global_load_dwordx4 v[40:43], v[20:21], off
	v_and_or_b32 v18, v23, s10, v18
	v_mul_lo_u32 v18, v18, s11
	v_add3_u32 v30, 0, v18, v16
	v_add_u32_e32 v24, 1536, v4
	v_add_u32_e32 v25, 12288, v1
	v_lshrrev_b32_e32 v16, 6, v24
	v_lshlrev_b32_e32 v20, 1, v25
	v_and_b32_e32 v21, 0x1fffff0, v16
	v_ashrrev_i32_e32 v23, 3, v24
	v_and_b32_e32 v16, 0x70, v20
	v_or_b32_e32 v20, s48, v21
	v_bfe_u32 v18, v24, 3, 6
	v_and_b32_e32 v22, 64, v23
	v_lshlrev_b32_e32 v20, 7, v20
	v_or3_b32 v20, v20, v22, v18
	v_ashrrev_i32_e32 v21, 31, v20
	v_lshlrev_b64 v[20:21], 7, v[20:21]
	v_lshl_add_u64 v[20:21], s[6:7], 0, v[20:21]
	v_lshl_add_u64 v[20:21], v[20:21], 0, v[16:17]
	global_load_dwordx4 v[44:47], v[20:21], off
	v_and_or_b32 v18, v23, s10, v18
	v_mul_lo_u32 v18, v18, s11
	v_add3_u32 v31, 0, v18, v16
	s_waitcnt vmcnt(3)
	ds_write_b128 v28, v[32:35]
	s_waitcnt vmcnt(2)
	ds_write_b128 v29, v[36:39]
	s_waitcnt vmcnt(1)
	ds_write_b128 v30, v[40:43]
	s_waitcnt vmcnt(0)
	ds_write_b128 v31, v[44:47]

; #define LAS __attribute__((address_space(3)))
; template <int PASS>
; __device__ __forceinline__ void lru_phase(Frame& F, const Params& p) {
;     ...
;     const int wg = (F.bx >> 4) * NWAVES + F.wave, NWG = (F.G >> 4) * NWAVES;
;     const int nitems = 2 * 65 * 8;
;     {
;         LAS unsigned char* pf = F.lds + 40960 + NWAVES * (32 * 68 * 4) + F.wave * 4480;
;         int it = wg;
;         if (PASS == 2) while (it < nitems && ((it >> 3) % 65) == 64) it += NWG;
;         if (it < nitems) { int ln = F.lane; asm volatile("" : "+v"(ln)); lru_prefetch(F.ws, pf, ln, head, it); }
.LBB0_692:
	s_or_b64 exec, exec, s[8:9]
	s_bfe_u32 s17, s70, 0x30006
	s_lshl_b32 s18, s17, 5
	s_add_i32 s18, s18, -1
	s_add_u32 s19, s56, 0x14000000
	s_addc_u32 s30, s57, 0
	s_mov_b32 s5, 0
	s_mov_b32 s31, 0x1e000000
	s_lshl_b32 s34, s11, 1
	s_movk_i32 s35, 0x118
	v_mov_b32_e32 v89, 0
	s_movk_i32 s36, 0xd8
	s_add_i32 s37, s46, 0x400
	s_movk_i32 s38, 0x98
	s_add_i32 s39, s46, 0x800
	s_movk_i32 s40, 0x58
	s_add_i32 s41, s46, 0xc00
	s_movk_i32 s42, 0x100
	s_add_i32 s43, s46, 0x1000
	s_movk_i32 s49, 0xfe
	s_movk_i32 s55, 0x110
	s_movk_i32 s61, 0x440
	s_movk_i32 s69, 0x90
	v_mov_b32_e32 v109, 0xff
	s_lshl_b32 s79, s16, 2
	s_mov_b32 s62, s47
	s_waitcnt vmcnt(0)
	s_branch .LBB0_694

; #define LAS __attribute__((address_space(3)))
; __device__ __forceinline__ void lru_prefetch(const unsigned char* ws, LAS unsigned char* pf, int lane, int head, int item) {
;     const int rc = item & 7, col = (item >> 3) % 65, b = (item >> 3) / 65;
;     const bf16* vbase; size_t rstride;
;     if (col < 64) { vbase = (const bf16*)(ws + WS_V) + ((size_t)(b * SEQ + col) * LRUW + head * 64); rstride = (size_t)64 * LRUW; }
;     else { vbase = (const bf16*)(ws + WS_VC) + ((size_t)(b * CTXL) * LRUW + head * 64); rstride = LRUW; }
; #pragma unroll
;     for (int i = 0; i < 5; ++i) {
;         const int pi = lane + 64 * i, rr = pi >> 3, sl = pi & 7, c = sl ^ ((rr >> 1) & 7);
;         int g = rc * 32 - 1 + rr; g = g < 0 ? 0 : (g > 255 ? 255 : g);
;         if (pi < 280) __builtin_amdgcn_global_load_lds((const unsigned*)(vbase + (size_t)g * rstride + c * 8), (LAS unsigned*)(pf + i * 1024), 16, 0, 0);
;     }
; template <int PASS>
; __device__ __forceinline__ void lru_item(Frame& F, const LAS bf16* lw, const LAS float* prm, const LAS float* cwl, LAS float* xs, LAS unsigned char* pf, int head, int item, int nitem) {
;     ...
;     asm volatile("s_waitcnt vmcnt(0)" ::: "memory");
;     u32x4 vw[4][4];
; #pragma unroll
;     for (int k = 0; k < 4; ++k) {
;         const int rr = r - 1 + k; const bool ok = (rr >= 0) && (rr < 256);
;         const int row = t + k;
; #pragma unroll
;         for (int ks = 0; ks < 4; ++ks) { u32x4 w = *(const LAS u32x4*)(pf + row * 128 + (((2 * ks + hh) ^ ((row >> 1) & 7)) * 16)); if (!ok) w = (u32x4){0u, 0u, 0u, 0u}; vw[k][ks] = w; }
;     }
.LBB0_694:
	v_mov_b32_e32 v111, v108
	s_waitcnt vmcnt(4)
	s_add_i32 s80, s62, s45
	v_and_b32_e32 v110, 31, v111
	v_ashrrev_i32_e32 v112, 5, v111
	v_lshrrev_b32_e32 v1, 1, v111
	v_lshl_add_u32 v0, v110, 7, s46
	v_bitop3_b32 v2, v1, v112, 7 bitop3:0x6c
	v_add_u32_e32 v32, 2, v112
	v_lshl_add_u32 v2, v2, 4, v0
	v_bitop3_b32 v3, v32, v1, 7 bitop3:0x78
	v_add_u32_e32 v33, 4, v112
	v_add_u32_e32 v34, 6, v112
	v_lshl_add_u32 v3, v3, 4, v0
	ds_read_b128 v[20:23], v2
	s_waitcnt lgkmcnt(0)
	ds_read_b128 v[8:11], v3
	v_bitop3_b32 v2, v33, v1, 7 bitop3:0x78
	v_bitop3_b32 v1, v34, v1, 7 bitop3:0x78
	v_lshl_add_u32 v2, v2, 4, v0
	v_lshl_add_u32 v0, v1, 4, v0
	ds_read_b128 v[24:27], v2
	ds_read_b128 v[16:19], v0
	v_add_u32_e32 v0, 1, v110
	v_lshl_add_u32 v1, v0, 7, s46
	v_lshrrev_b32_e32 v0, 1, v0
	v_bitop3_b32 v2, v0, v112, 7 bitop3:0x6c
	v_add_u32_e32 v35, 2, v110
	v_lshl_add_u32 v2, v2, 4, v1
	v_bitop3_b32 v3, v0, v32, 7 bitop3:0x6c
	v_lshl_add_u32 v36, v35, 7, s46
	v_lshrrev_b32_e32 v35, 1, v35
	v_lshl_add_u32 v3, v3, 4, v1
	ds_read_b128 v[28:31], v2
	ds_read_b128 v[12:15], v3
	v_bitop3_b32 v2, v0, v33, 7 bitop3:0x6c
	v_bitop3_b32 v0, v0, v34, 7 bitop3:0x6c
	v_bitop3_b32 v37, v35, v112, 7 bitop3:0x6c
	v_lshl_add_u32 v2, v2, 4, v1
	v_lshl_add_u32 v0, v0, 4, v1
	v_lshl_add_u32 v37, v37, 4, v36
	v_bitop3_b32 v38, v35, v32, 7 bitop3:0x6c
	ds_read_b128 v[4:7], v2
	ds_read_b128 v[0:3], v0
	v_lshl_add_u32 v38, v38, 4, v36
	ds_read_b128 v[60:63], v37
	ds_read_b128 v[44:47], v38
	v_bitop3_b32 v37, v35, v33, 7 bitop3:0x6c
	v_bitop3_b32 v35, v35, v34, 7 bitop3:0x6c
	v_lshl_add_u32 v37, v37, 4, v36
	v_lshl_add_u32 v35, v35, 4, v36
	ds_read_b128 v[52:55], v37
	ds_read_b128 v[36:39], v35
	v_add_u32_e32 v35, 3, v110
	v_lshl_add_u32 v48, v35, 7, s46
	v_lshrrev_b32_e32 v35, 1, v35
	v_bitop3_b32 v40, v35, v112, 7 bitop3:0x6c
	v_bitop3_b32 v32, v35, v32, 7 bitop3:0x6c
	v_lshl_add_u32 v40, v40, 4, v48
	v_lshl_add_u32 v32, v32, 4, v48
	ds_read_b128 v[56:59], v40
	ds_read_b128 v[40:43], v32
	v_bitop3_b32 v32, v35, v33, 7 bitop3:0x6c
	v_bitop3_b32 v33, v35, v34, 7 bitop3:0x6c
	v_lshl_add_u32 v32, v32, 4, v48
	v_lshl_add_u32 v33, v33, 4, v48
	ds_read_b128 v[48:51], v32
	ds_read_b128 v[32:35], v33
	s_cmpk_gt_i32 s80, 0x40f
	s_waitcnt lgkmcnt(0)
	s_cselect_b64 s[6:7], -1, 0
	s_cmpk_lt_i32 s80, 0x410
	s_cselect_b32 s12, s80, -1
	s_cmp_lt_i32 s12, 0
	s_cbranch_scc1 .LBB0_702
	s_lshr_b32 s4, s12, 3
	s_mul_hi_u32 s8, s4, 0x3f03f04
	s_mulk_i32 s8, 0x41
	s_sub_i32 s4, s4, s8
	s_mul_hi_u32 s8, s12, 0xfc0fc0fd
	s_lshr_b32 s10, s8, 9
	s_cmp_lt_u32 s4, 64
	s_cselect_b64 s[8:9], -1, 0
	s_lshl_b32 s13, s10, 8
	s_lshl_b32 s10, s10, 14
	s_or_b32 s4, s10, s4
	s_and_b64 s[10:11], s[8:9], exec
	s_cselect_b32 s10, s31, 0x3e300000
	s_cselect_b32 s4, s4, s13
	s_add_u32 s13, s56, s10
	s_addc_u32 s63, s57, 0
	s_lshl_b64 s[10:11], s[4:5], 11
	s_add_u32 s4, s13, s10
	s_addc_u32 s11, s63, s11
	s_add_u32 s10, s4, s34
	s_addc_u32 s11, s11, 0
	s_lshl_b32 s4, s12, 5
	s_and_b32 s4, s4, 0xe0
	v_lshrrev_b32_e32 v64, 4, v111
	s_add_i32 s4, s4, -1
	v_cmp_gt_i32_e32 vcc, s35, v111
	v_xor_b32_e32 v64, v64, v111
	s_and_saveexec_b64 s[12:13], vcc
	s_cbranch_execnz .LBB0_710
	s_or_b64 exec, exec, s[12:13]
	v_cmp_gt_i32_e32 vcc, s36, v111
	s_and_saveexec_b64 s[12:13], vcc
	s_cbranch_execnz .LBB0_711

; #define LAS __attribute__((address_space(3)))
; template <int PASS>
; __device__ __forceinline__ void lru_phase(Frame& F, const Params& p) {
;     ...
;     const int wg = (F.bx >> 4) * NWAVES + F.wave, NWG = (F.G >> 4) * NWAVES;
;     const int nitems = 2 * 65 * 8;
;     {
;         LAS unsigned char* pf = F.lds + 40960 + NWAVES * (32 * 68 * 4) + F.wave * 4480;
;         int it = wg;
;         if (PASS == 2) while (it < nitems && ((it >> 3) % 65) == 64) it += NWG;
;         if (it < nitems) { int ln = F.lane; asm volatile("" : "+v"(ln)); lru_prefetch(F.ws, pf, ln, head, it); }
.LBB0_899:
	s_cmpk_gt_i32 s47, 0x40f
	s_cbranch_scc1 .LBB0_918
	s_lshl_b32 s4, s48, 6
	s_lshl_b32 s6, s48, 8
	s_add_u32 s6, s56, s6
	s_addc_u32 s7, s57, 0
	s_add_u32 s6, s6, 0x15200000
	s_addc_u32 s7, s7, 0
	s_lshl_b32 s8, s48, 7
	s_add_u32 s10, s56, s8
	s_addc_u32 s11, s57, 0
	s_add_u32 s8, s10, 0x22000000
	s_addc_u32 s9, s11, 0
	s_add_u32 s10, s10, 0x3a000000
	s_mov_b32 s5, 0
	s_addc_u32 s11, s11, 0
	s_mov_b32 s34, 0x1e000000
	s_lshl_b32 s35, s4, 1
	s_movk_i32 s36, 0x118
	s_movk_i32 s37, 0xff
	v_mov_b32_e32 v89, 0
	s_movk_i32 s38, 0xd8
	s_add_i32 s39, s46, 0x400
	s_movk_i32 s40, 0x98
	s_add_i32 s41, s46, 0x800
	s_movk_i32 s42, 0x58
	s_add_i32 s43, s46, 0xc00
	s_add_i32 s48, s46, 0x1000
	s_movk_i32 s49, 0xfe
	s_movk_i32 s55, 0x110
	s_movk_i32 s61, 0x440
	v_mov_b32_e32 v115, 0xff
	s_waitcnt vmcnt(0)
	s_branch .LBB0_903

; #define LAS __attribute__((address_space(3)))
; template <int PASS>
; __device__ __forceinline__ void lru_item(Frame& F, const LAS bf16* lw, const LAS float* prm, const LAS float* cwl, LAS float* xs, LAS unsigned char* pf, int head, int item, int nitem) {
;     const int rc = item & 7, col = (item >> 3) % 65, b = (item >> 3) / 65;
;     int lane = F.lane; asm volatile("" : "+v"(lane));
;     const int t = lane & 31, hh = lane >> 5;
;     const int r0 = rc * 32, r = r0 + t;
;     const int q = (col < 64) ? (8 + col * 8 + rc) : rc;
;     asm volatile("s_waitcnt vmcnt(0)" ::: "memory");
;     u32x4 vw[4][4];
; #pragma unroll
;     for (int k = 0; k < 4; ++k) {
;         const int rr = r - 1 + k; const bool ok = (rr >= 0) && (rr < 256);
;         const int row = t + k;
; #pragma unroll
;         for (int ks = 0; ks < 4; ++ks) { u32x4 w = *(const LAS u32x4*)(pf + row * 128 + (((2 * ks + hh) ^ ((row >> 1) & 7)) * 16)); if (!ok) w = (u32x4){0u, 0u, 0u, 0u}; vw[k][ks] = w; }
;     }
.LBB0_907:
	v_mov_b32_e32 v144, v114
	s_waitcnt vmcnt(4)
	s_cmp_lt_i32 s28, 0
	v_and_b32_e32 v121, 31, v144
	v_ashrrev_i32_e32 v116, 5, v144
	v_lshrrev_b32_e32 v1, 1, v144
	v_lshl_add_u32 v0, v121, 7, s46
	v_bitop3_b32 v2, v1, v116, 7 bitop3:0x6c
	v_add_u32_e32 v48, 2, v116
	v_lshl_add_u32 v2, v2, 4, v0
	v_bitop3_b32 v3, v48, v1, 7 bitop3:0x78
	v_add_u32_e32 v56, 4, v116
	v_add_u32_e32 v57, 6, v116
	v_lshl_add_u32 v3, v3, 4, v0
	ds_read_b128 v[12:15], v2
	ds_read_b128 v[16:19], v3
	v_bitop3_b32 v2, v56, v1, 7 bitop3:0x78
	v_bitop3_b32 v1, v57, v1, 7 bitop3:0x78
	v_lshl_add_u32 v2, v2, 4, v0
	v_lshl_add_u32 v0, v1, 4, v0
	ds_read_b128 v[20:23], v2
	ds_read_b128 v[28:31], v0
	v_add_u32_e32 v0, 1, v121
	v_lshl_add_u32 v1, v0, 7, s46
	v_lshrrev_b32_e32 v0, 1, v0
	v_bitop3_b32 v2, v0, v116, 7 bitop3:0x6c
	v_add_u32_e32 v32, 2, v121
	v_add_u32_e32 v49, 3, v121
	v_lshl_add_u32 v2, v2, 4, v1
	v_bitop3_b32 v3, v0, v48, 7 bitop3:0x6c
	v_lshrrev_b32_e32 v41, 1, v32
	v_lshrrev_b32_e32 v59, 1, v49
	v_lshl_add_u32 v3, v3, 4, v1
	ds_read_b128 v[24:27], v2
	ds_read_b128 v[8:11], v3
	v_bitop3_b32 v2, v0, v56, 7 bitop3:0x6c
	v_bitop3_b32 v0, v0, v57, 7 bitop3:0x6c
	v_lshl_add_u32 v40, v32, 7, s46
	v_bitop3_b32 v32, v41, v116, 7 bitop3:0x6c
	v_bitop3_b32 v33, v41, v48, 7 bitop3:0x6c
	v_bitop3_b32 v42, v41, v56, 7 bitop3:0x6c
	v_bitop3_b32 v41, v41, v57, 7 bitop3:0x6c
	v_lshl_add_u32 v58, v49, 7, s46
	v_bitop3_b32 v49, v59, v116, 7 bitop3:0x6c
	v_bitop3_b32 v48, v59, v48, 7 bitop3:0x6c
	v_bitop3_b32 v56, v59, v56, 7 bitop3:0x6c
	v_bitop3_b32 v57, v59, v57, 7 bitop3:0x6c
	v_lshl_add_u32 v2, v2, 4, v1
	v_lshl_add_u32 v0, v0, 4, v1
	v_lshl_add_u32 v32, v32, 4, v40
	v_lshl_add_u32 v36, v33, 4, v40
	v_lshl_add_u32 v42, v42, 4, v40
	v_lshl_add_u32 v44, v41, 4, v40
	v_lshl_add_u32 v49, v49, 4, v58
	v_lshl_add_u32 v52, v48, 4, v58
	v_lshl_add_u32 v56, v56, 4, v58
	v_lshl_add_u32 v60, v57, 4, v58
	ds_read_b128 v[4:7], v2
	ds_read_b128 v[0:3], v0
	ds_read_b128 v[32:35], v32
	ds_read_b128 v[36:39], v36
	ds_read_b128 v[40:43], v42
	ds_read_b128 v[44:47], v44
	ds_read_b128 v[48:51], v49
	ds_read_b128 v[52:55], v52
	ds_read_b128 v[56:59], v56
	ds_read_b128 v[60:63], v60
	s_waitcnt lgkmcnt(0)
	s_cbranch_scc1 .LBB0_902
	s_lshr_b32 s4, s28, 3
	s_add_i32 s16, s4, 0xffffffbf
	s_cmpk_lt_u32 s28, 0x208
	s_cselect_b32 s4, s4, s16
	s_cmp_lt_u32 s4, 64
	s_cselect_b64 s[16:17], -1, 0
	s_cmpk_gt_u32 s28, 0x207
	s_cselect_b32 s18, 0x4000, 0
	s_cselect_b32 s29, 0x100, 0
	s_or_b32 s4, s4, s18
	s_and_b64 s[18:19], s[16:17], exec
	s_cselect_b32 s18, s34, 0x3e300000
	s_cselect_b32 s4, s4, s29
	s_add_u32 s29, s56, s18
	s_addc_u32 s63, s57, 0
	s_lshl_b64 s[18:19], s[4:5], 11
	s_add_u32 s4, s29, s18
	s_addc_u32 s19, s63, s19
	s_add_u32 s18, s4, s35
	s_addc_u32 s19, s19, 0
	s_lshl_b32 s4, s28, 5
	s_and_b32 s4, s4, 0xe0
	v_lshrrev_b32_e32 v64, 4, v144
	s_add_i32 s4, s4, -1
	v_cmp_gt_i32_e32 vcc, s36, v144
	v_xor_b32_e32 v64, v64, v144
	s_and_saveexec_b64 s[28:29], vcc
	s_cbranch_execnz .LBB0_913
	s_or_b64 exec, exec, s[28:29]
	v_cmp_gt_i32_e32 vcc, s38, v144
	s_and_saveexec_b64 s[28:29], vcc
	s_cbranch_execnz .LBB0_914

; __device__ __forceinline__ void cf_load(CfIn& r, const unsigned char* ws, int tok, int lane) {
; #pragma unroll
;     for (int c = 0; c < 8; ++c) { const int* pd = (const int*)(ws + WS_PD) + ((size_t)c * NTOK + tok) * 128; r.d0[c] = pd[lane]; r.d1[c] = pd[64 + lane]; }
;     r.fs = ((const float*)(ws + WS_FS))[tok]; r.s0 = ((const int*)(ws + WS_FS + (1u << 20)))[2 * tok]; r.s1 = ((const int*)(ws + WS_FS + (1u << 20)))[2 * tok + 1];
;     r.u0 = ((const float*)(ws + WS_SELU))[(size_t)tok * 128 + lane]; r.u1 = ((const float*)(ws + WS_SELU))[(size_t)tok * 128 + 64 + lane];
;     r.g0 = ((const float*)(ws + WS_SELG))[(size_t)tok * 128 + lane]; r.g1 = ((const float*)(ws + WS_SELG))[(size_t)tok * 128 + 64 + lane];
; }
; __device__ __forceinline__ void peer_cf(Frame& F) {
;     const int lane = F.lane, gw = F.bx * NWAVES + F.wave, NGW = F.G * NWAVES;
;     CfIn rn;
;     if (gw < NTOK) cf_load(rn, F.ws, gw, lane);
;     for (int tok = gw; tok < NTOK; tok += NGW) {
;         const CfIn r = rn;
;         if (tok + NGW < NTOK) cf_load(rn, F.ws, tok + NGW, lane);
.LBB0_2074:
	s_or_b64 exec, exec, s[38:39]
	s_waitcnt lgkmcnt(0)
	v_cndmask_b32_e64 v0, 0, 1, s[88:89]
	s_mov_b32 s86, s68
	v_cmp_ne_u32_e64 s[38:39], 1, v0
	s_andn2_b64 vcc, exec, s[88:89]
	s_barrier
	v_mbcnt_lo_u32_b32 v4, -1, 0
	v_mbcnt_hi_u32_b32 v4, -1, v4
	s_cbranch_vccnz .LBB0_2081
	s_ashr_i32 s61, s60, 31
	s_lshl_b64 s[40:41], s[60:61], 9
	s_add_u32 s40, s3, s40
	v_ashrrev_i32_e32 v5, 31, v4
	s_addc_u32 s41, s55, s41
	v_lshlrev_b64 v[10:11], 2, v[4:5]
	v_lshl_add_u64 v[2:3], s[40:41], 0, v[10:11]
	s_lshl_b64 s[40:41], s[60:61], 2
	s_add_u32 s40, s56, s40
	s_addc_u32 s41, s57, s41
	s_waitcnt vmcnt(15)
	v_add_co_u32_e32 v16, vcc, 0x1000000, v2
	s_add_u32 s62, s56, 0x1c100000
	s_nop 0
	v_addc_co_u32_e32 v17, vcc, 0, v3, vcc
	s_addc_u32 s63, s57, 0
	s_lshl_b32 s42, s60, 1
	v_add_co_u32_e32 v18, vcc, 0x2000000, v2
	s_ashr_i32 s43, s42, 31
	s_nop 0
	v_addc_co_u32_e32 v19, vcc, 0, v3, vcc
	s_lshl_b64 s[42:43], s[42:43], 2
	s_waitcnt vmcnt(14)
	v_add_co_u32_e32 v20, vcc, 0x3000000, v2
	s_add_u32 s42, s62, s42
	s_nop 0
	v_addc_co_u32_e32 v21, vcc, 0, v3, vcc
	s_addc_u32 s43, s63, s43
	s_waitcnt vmcnt(13)
	v_add_co_u32_e32 v24, vcc, 0x4000000, v2
	s_add_u32 s44, s56, 0xe200000
	s_nop 0
	v_addc_co_u32_e32 v25, vcc, 0, v3, vcc
	s_addc_u32 s45, s57, 0
	s_lshl_b64 s[46:47], s[60:61], 7
	v_add_co_u32_e32 v26, vcc, 0x5000000, v2
	v_lshl_add_u64 v[0:1], s[46:47], 0, v[4:5]
	s_nop 0
	v_addc_co_u32_e32 v27, vcc, 0, v3, vcc
	s_waitcnt vmcnt(11)
	v_lshlrev_b64 v[32:33], 2, v[0:1]
	s_mov_b64 s[46:47], 0x100
	v_add_co_u32_e32 v28, vcc, 0x6000000, v2
	s_waitcnt vmcnt(6)
	v_lshl_add_u64 v[54:55], v[32:33], 0, s[46:47]
	s_add_u32 s46, s56, 0xd200000
	v_addc_co_u32_e32 v29, vcc, 0, v3, vcc
	s_addc_u32 s47, s57, 0
	v_add_co_u32_e32 v30, vcc, 0x7000000, v2
	v_bfrev_b32_e32 v6, 56
	v_lshl_add_u64 v[8:9], s[46:47], 0, v[32:33]
	v_lshl_add_u64 v[34:35], s[46:47], 0, v[54:55]
	v_addc_co_u32_e32 v31, vcc, 0, v3, vcc
	v_mov_b32_e32 v14, 0
	global_load_dword v6, v6, s[40:41]
	s_nop 0
	global_load_dwordx2 v[12:13], v14, s[42:43]
	global_load_dword v22, v[8:9], off
	global_load_dword v23, v[34:35], off
	global_load_dword v7, v[24:25], off offset:256
	global_load_dword v38, v[26:27], off offset:256
	s_nop 0
	global_load_dword v9, v[28:29], off offset:256
	global_load_dword v34, v[30:31], off offset:256
	global_load_dword v43, v[2:3], off offset:256
	global_load_dword v47, v[16:17], off offset:256
	global_load_dword v48, v[18:19], off offset:256
	global_load_dword v51, v[20:21], off offset:256
	global_load_dword v37, v[24:25], off
	global_load_dword v40, v[26:27], off
	global_load_dword v41, v[28:29], off
	global_load_dword v46, v[30:31], off
	global_load_dword v45, v[2:3], off
	global_load_dword v49, v[16:17], off
	global_load_dword v50, v[18:19], off
	global_load_dword v53, v[20:21], off
	v_lshl_add_u64 v[2:3], s[44:45], 0, v[32:33]
	v_lshl_add_u64 v[16:17], s[44:45], 0, v[54:55]
	global_load_dword v2, v[2:3], off
	s_nop 0
	global_load_dword v8, v[16:17], off
	s_add_u32 s61, s56, 0x37000000
	s_addc_u32 s68, s57, 0
	s_add_i32 s46, s60, s54
	s_lshl_b32 s2, s2, 4
	s_lshl_b32 s3, s86, 1
	s_ashr_i32 s55, s54, 31
	s_ashr_i32 s47, s46, 31
	s_add_i32 s2, s2, s3
	s_lshl_b32 s69, s58, 4
	s_lshl_b64 s[42:43], s[54:55], 7
	s_lshl_b64 s[44:45], s[46:47], 2
	s_add_u32 s71, s44, 0x1c000000
	v_lshlrev_b32_e32 v3, 2, v4
	s_addc_u32 s78, s45, 0
	s_lshl_b64 s[46:47], s[46:47], 9
	v_cmp_eq_u32_e64 s[40:41], 0, v4
	v_xor_b32_e32 v15, 4, v3
	v_xor_b32_e32 v16, 8, v3
	v_xor_b32_e32 v17, 16, v3
	v_xor_b32_e32 v18, 32, v3
	v_xor_b32_e32 v19, 64, v3
	v_xor_b32_e32 v20, 0x80, v3
	s_lshl_b64 s[44:45], s[54:55], 2
	v_lshl_add_u64 v[4:5], s[46:47], 0, v[10:11]
	s_lshl_b64 s[46:47], s[54:55], 9
	s_mov_b32 s55, 0x42fe0000
	s_mov_b32 s79, 0x36000000
	v_mov_b32_e32 v21, 0x37000000
	v_mov_b32_e32 v3, 0x3d800000
	s_mov_b32 s80, s60
	s_waitcnt vmcnt(21)
	v_mov_b32_e32 v32, v6
	s_waitcnt vmcnt(20)
	v_mov_b64_e32 v[10:11], v[12:13]
	s_waitcnt vmcnt(19)
	v_mov_b32_e32 v55, v22
	s_waitcnt vmcnt(18)
	v_mov_b32_e32 v54, v23
	s_waitcnt vmcnt(17)
	v_mov_b32_e32 v25, v7
	s_waitcnt vmcnt(16)
	v_mov_b32_e32 v26, v38
	s_waitcnt vmcnt(15)
	v_mov_b32_e32 v27, v9
	s_waitcnt vmcnt(14)
	v_mov_b32_e32 v52, v34
	s_waitcnt vmcnt(13)
	v_mov_b32_e32 v33, v43
	s_waitcnt vmcnt(12)
	v_mov_b32_e32 v35, v47
	s_waitcnt vmcnt(11)
	v_mov_b32_e32 v36, v48
	s_waitcnt vmcnt(10)
	v_mov_b32_e32 v24, v51
	s_waitcnt vmcnt(9)
	v_mov_b32_e32 v29, v37
	s_waitcnt vmcnt(8)
	v_mov_b32_e32 v30, v40
	s_waitcnt vmcnt(7)
	v_mov_b32_e32 v31, v41
	s_waitcnt vmcnt(6)
	v_mov_b32_e32 v56, v46
	s_waitcnt vmcnt(5)
	v_mov_b32_e32 v39, v45
	s_waitcnt vmcnt(4)
	v_mov_b32_e32 v42, v49
	s_waitcnt vmcnt(3)
	v_mov_b32_e32 v44, v50
	s_waitcnt vmcnt(2)
	v_mov_b32_e32 v28, v53
	s_waitcnt vmcnt(0)
	s_branch .LBB0_2077

; __device__ __forceinline__ void cf_load(CfIn& r, const unsigned char* ws, int tok, int lane) {
; #pragma unroll
;     for (int c = 0; c < 8; ++c) { const int* pd = (const int*)(ws + WS_PD) + ((size_t)c * NTOK + tok) * 128; r.d0[c] = pd[lane]; r.d1[c] = pd[64 + lane]; }
;     r.fs = ((const float*)(ws + WS_FS))[tok]; r.s0 = ((const int*)(ws + WS_FS + (1u << 20)))[2 * tok]; r.s1 = ((const int*)(ws + WS_FS + (1u << 20)))[2 * tok + 1];
;     r.u0 = ((const float*)(ws + WS_SELU))[(size_t)tok * 128 + lane]; r.u1 = ((const float*)(ws + WS_SELU))[(size_t)tok * 128 + 64 + lane];
;     r.g0 = ((const float*)(ws + WS_SELG))[(size_t)tok * 128 + lane]; r.g1 = ((const float*)(ws + WS_SELG))[(size_t)tok * 128 + 64 + lane];
; }
; __device__ __forceinline__ void peer_cf(Frame& F) {
;     ...
;     for (int tok = gw; tok < NTOK; tok += NGW) {
;         const CfIn r = rn;
;         if (tok + NGW < NTOK) cf_load(rn, F.ws, tok + NGW, lane);
.LBB0_2077:
	s_add_i32 s80, s80, s54
	s_cmpk_gt_i32 s80, 0x7fff
	s_cselect_b64 s[48:49], -1, 0
	s_and_b64 vcc, exec, s[48:49]
	s_nop 0
	v_mov_b32_e32 v57, v8
	v_mov_b32_e32 v58, v2
	s_cbranch_vccnz .LBB0_2079
	v_lshl_add_u64 v[54:55], s[56:57], 0, v[4:5]
	v_add_co_u32_e32 v10, vcc, 0x1e000000, v54
	s_add_u32 s50, s56, s71
	s_nop 0
	v_addc_co_u32_e32 v11, vcc, 0, v55, vcc
	v_add_co_u32_e32 v56, vcc, 0x1f000000, v54
	s_addc_u32 s51, s57, s78
	s_nop 0
	v_addc_co_u32_e32 v57, vcc, 0, v55, vcc
	v_add_co_u32_e32 v58, vcc, 0x20000000, v54
	s_add_i32 s82, s69, s2
	s_nop 0
	v_addc_co_u32_e32 v59, vcc, 0, v55, vcc
	v_add_co_u32_e32 v24, vcc, 0x21000000, v54
	s_ashr_i32 s83, s82, 31
	s_nop 0
	v_addc_co_u32_e32 v25, vcc, 0, v55, vcc
	v_add_co_u32_e32 v26, vcc, 0x22000000, v54
	s_lshl_b64 s[82:83], s[82:83], 2
	s_nop 0
	v_addc_co_u32_e32 v27, vcc, 0, v55, vcc
	v_add_co_u32_e32 v32, vcc, 0x23000000, v54
	s_add_u32 s82, s62, s82
	s_nop 0
	v_addc_co_u32_e32 v33, vcc, 0, v55, vcc
	v_add_co_u32_e32 v60, vcc, 0x24000000, v54
	s_addc_u32 s83, s63, s83
	s_nop 0
	v_addc_co_u32_e32 v61, vcc, 0, v55, vcc
	global_load_dword v28, v[24:25], off
	s_nop 0
	global_load_dword v24, v[24:25], off offset:256
	s_nop 0
	global_load_dword v29, v[26:27], off
	global_load_dword v25, v[26:27], off offset:256
	global_load_dword v30, v[32:33], off
	s_nop 0
	global_load_dword v26, v[32:33], off offset:256
	global_load_dword v31, v[60:61], off
	global_load_dword v27, v[60:61], off offset:256
	v_add_co_u32_e32 v60, vcc, 0x25000000, v54
	global_load_dword v39, v[10:11], off
	global_load_dword v33, v[10:11], off offset:256
	global_load_dword v42, v[56:57], off
	global_load_dword v35, v[56:57], off offset:256
	global_load_dword v44, v[58:59], off
	global_load_dword v36, v[58:59], off offset:256
	global_load_dword v32, v14, s[50:51]
	global_load_dwordx2 v[10:11], v14, s[82:83]
	v_addc_co_u32_e32 v61, vcc, 0, v55, vcc
	v_add_co_u32_e32 v62, vcc, 0xe200000, v54
	s_nop 1
	v_addc_co_u32_e32 v63, vcc, 0, v55, vcc
	v_add_co_u32_e32 v64, vcc, 0xd200000, v54
	s_nop 1
	v_addc_co_u32_e32 v65, vcc, 0, v55, vcc
	global_load_dword v56, v[60:61], off
	global_load_dword v52, v[60:61], off offset:256
	global_load_dword v58, v[62:63], off
	global_load_dword v57, v[62:63], off offset:256
	global_load_dword v55, v[64:65], off
	global_load_dword v54, v[64:65], off offset:256

; template <bool VPASS>
; __device__ __forceinline__ PeerVisit visit_load(const unsigned char* ws, const unsigned char* FQc, int tok, int lane) {
;     PeerVisit v; const int pg = lane >> 3;
;     const u32x4* ep = (const u32x4*)((const int*)(ws + WS_SELE) + (size_t)tok * 128 + pg * 16);
; #pragma unroll
;     for (int q = 0; q < 4; ++q) v.e[q] = ep[q];
;     if (VPASS) { v.x = *(const u32x4*)(ws + WS_CFQ + (size_t)tok * 128 + pg * 16); v.x2 = v.x; v.sc = ((const float*)(ws + WS_CS))[2 * tok]; v.cs = ((const int*)(ws + WS_CS))[2 * tok + 1]; }
;     else { const u32x4* fp = (const u32x4*)(FQc + (size_t)tok * D + (lane & 7) * 32); v.x = fp[0]; v.x2 = fp[1]; v.sc = 0.f; v.cs = 0; }
;     return v;
; }
; __device__ __forceinline__ void rows16_load(u32x4 (&w)[16], const unsigned char* T, const PeerVisit& v, int lane) {
;     const int pc = (lane & 7) * 16;
; #pragma unroll
;     for (int q = 0; q < 4; ++q) {
;         w[4 * q + 0] = *(const u32x4*)(T + (v.e[q].x * 128u + (unsigned)pc)); w[4 * q + 1] = *(const u32x4*)(T + (v.e[q].y * 128u + (unsigned)pc));
;         w[4 * q + 2] = *(const u32x4*)(T + (v.e[q].z * 128u + (unsigned)pc)); w[4 * q + 3] = *(const u32x4*)(T + (v.e[q].w * 128u + (unsigned)pc));
;     }
; }
; template <bool VPASS>
; __device__ __forceinline__ void peer_pass(Frame& F, int c, int rank, int nblk) {
;     const unsigned char* T = F.ws + (VPASS ? WS_PV : WS_PU) + (size_t)c * 16384 * 128; const unsigned char* FQc = F.ws + WS_FQ + c * 256;
;     int* PD = (int*)(F.ws + WS_PD) + (size_t)c * NTOK * 128; bf16* PO = (bf16*)(F.ws + WS_PO) + c * 256;
;     const int t0 = rank * NWAVES + F.wave, step = nblk * NWAVES;
;     if (t0 >= NTOK) return;
;     const int nvis = (NTOK - t0 + step - 1) / step;
;     int lane = F.lane; asm volatile("" : "+v"(lane));
;     PeerVisit va = visit_load<VPASS>(F.ws, FQc, t0, lane), vb = va;
;     u32x4 wa[16], wb[16];
;     rows16_load(wa, T, va, lane);
;     if (nvis > 1) vb = visit_load<VPASS>(F.ws, FQc, t0 + step, lane);
.LBB0_2135:
	s_or_b64 exec, exec, s[2:3]
	s_andn2_b64 vcc, exec, s[76:77]
	s_waitcnt lgkmcnt(0)
	s_barrier
	v_mbcnt_lo_u32_b32 v186, -1, 0
	v_mbcnt_hi_u32_b32 v186, -1, v186
	s_cbranch_vccnz .LBB0_2156
	s_add_u32 s2, s56, s74
	s_addc_u32 s3, s57, s75
	s_add_u32 s2, s2, 0xa000000
	s_addc_u32 s3, s3, 0
	s_abs_i32 s40, s90
	v_cvt_f32_u32_e32 v0, s40
	s_sub_i32 s41, s90, s70
	s_add_i32 s42, s41, 0x7fff
	s_sub_i32 s41, 0xffff8001, s41
	v_rcp_iflag_f32_e32 v0, v0
	s_xor_b32 s44, s42, s90
	s_sub_i32 s43, 0, s40
	s_max_i32 s41, s42, s41
	v_mul_f32_e32 v0, 0x4f7ffffe, v0
	v_cvt_u32_f32_e32 v0, v0
	s_ashr_i32 s42, s44, 31
	s_waitcnt vmcnt(1)
	v_mov_b32_e32 v98, 0
	v_readfirstlane_b32 s44, v0
	s_mul_i32 s43, s43, s44
	s_mul_hi_u32 s43, s44, s43
	s_add_i32 s44, s44, s43
	s_mul_hi_u32 s43, s41, s44
	s_mul_i32 s44, s43, s40
	s_sub_i32 s41, s41, s44
	s_add_i32 s45, s43, 1
	s_sub_i32 s44, s41, s40
	s_cmp_ge_u32 s41, s40
	s_cselect_b32 s43, s45, s43
	s_cselect_b32 s41, s44, s41
	s_add_i32 s44, s43, 1
	s_cmp_ge_u32 s41, s40
	s_cselect_b32 s40, s44, s43
	s_xor_b32 s40, s40, s42
	s_sub_i32 s50, s40, s42
	s_add_u32 s51, s56, 0xc200000
	s_addc_u32 s55, s57, 0
	s_ashr_i32 s71, s70, 31
	s_lshl_b64 s[40:41], s[70:71], 7
	s_lshl_b64 s[42:43], s[70:71], 9
	v_lshlrev_b32_e32 v0, 1, v186
	s_add_u32 s42, s51, s42
	v_and_b32_e32 v96, -16, v0
	s_addc_u32 s43, s55, s43
	v_ashrrev_i32_e32 v97, 31, v96
	v_lshl_add_u64 v[0:1], v[96:97], 2, s[42:43]
	global_load_dwordx4 v[12:15], v[0:1], off
	global_load_dwordx4 v[8:11], v[0:1], off offset:16
	global_load_dwordx4 v[4:7], v[0:1], off offset:32
	s_nop 0
	global_load_dwordx4 v[0:3], v[0:1], off offset:48
	s_add_u32 s40, s66, s40
	s_addc_u32 s41, s67, s41
	v_lshlrev_b32_e32 v16, 4, v186
	s_add_u32 s61, s56, 0x37000000
	v_and_b32_e32 v18, 0x70, v16
	v_lshl_add_u64 v[16:17], s[40:41], 0, v[96:97]
	s_addc_u32 s68, s57, 0
	s_lshl_b32 s40, s70, 1
	s_ashr_i32 s41, s40, 31
	s_lshl_b64 s[40:41], s[40:41], 2
	s_add_u32 s40, s61, s40
	s_addc_u32 s41, s68, s41
	global_load_dwordx4 v[168:171], v[16:17], off
	global_load_dwordx2 v[182:183], v98, s[40:41]
	s_cmp_lt_i32 s50, 2
	s_waitcnt vmcnt(5)
	v_lshl_or_b32 v16, v12, 7, v18
	v_lshl_or_b32 v20, v13, 7, v18
	v_lshl_or_b32 v24, v14, 7, v18
	v_lshl_or_b32 v28, v15, 7, v18
	s_waitcnt vmcnt(4)
	v_lshl_or_b32 v32, v8, 7, v18
	v_lshl_or_b32 v36, v9, 7, v18
	v_lshl_or_b32 v40, v10, 7, v18
	v_lshl_or_b32 v44, v11, 7, v18
	s_waitcnt vmcnt(3)
	v_lshl_or_b32 v48, v4, 7, v18
	v_lshl_or_b32 v52, v5, 7, v18
	v_lshl_or_b32 v56, v6, 7, v18
	v_lshl_or_b32 v60, v7, 7, v18
	s_waitcnt vmcnt(2)
	v_lshl_or_b32 v64, v0, 7, v18
	v_lshl_or_b32 v68, v1, 7, v18
	v_lshl_or_b32 v72, v2, 7, v18
	v_lshl_or_b32 v73, v3, 7, v18
	global_load_dwordx4 v[16:19], v16, s[2:3]
	s_nop 0
	global_load_dwordx4 v[20:23], v20, s[2:3]
	s_nop 0
	global_load_dwordx4 v[24:27], v24, s[2:3]
	s_nop 0
	global_load_dwordx4 v[28:31], v28, s[2:3]
	s_nop 0
	global_load_dwordx4 v[32:35], v32, s[2:3]
	s_nop 0
	global_load_dwordx4 v[36:39], v36, s[2:3]
	s_nop 0
	global_load_dwordx4 v[40:43], v40, s[2:3]
	s_nop 0
	global_load_dwordx4 v[44:47], v44, s[2:3]
	s_nop 0
	global_load_dwordx4 v[48:51], v48, s[2:3]
	s_nop 0
	global_load_dwordx4 v[52:55], v52, s[2:3]
	s_nop 0
	global_load_dwordx4 v[56:59], v56, s[2:3]
	s_nop 0
	global_load_dwordx4 v[60:63], v60, s[2:3]
	s_nop 0
	global_load_dwordx4 v[64:67], v64, s[2:3]
	s_nop 0
	global_load_dwordx4 v[68:71], v68, s[2:3]
	s_nop 0
	global_load_dwordx4 v[80:83], v72, s[2:3]
	global_load_dwordx4 v[84:87], v73, s[2:3]
	v_mov_b64_e32 v[94:95], v[14:15]
	v_mov_b64_e32 v[78:79], v[10:11]
	v_mov_b64_e32 v[74:75], v[6:7]
	v_mov_b64_e32 v[90:91], v[2:3]
	s_waitcnt vmcnt(17)
	v_mov_b64_e32 v[160:161], v[168:169]
	v_mov_b64_e32 v[92:93], v[12:13]
	v_mov_b64_e32 v[76:77], v[8:9]
	v_mov_b64_e32 v[72:73], v[4:5]
	v_mov_b64_e32 v[88:89], v[0:1]
	v_mov_b64_e32 v[162:163], v[170:171]
	s_waitcnt vmcnt(0)
	v_mov_b32_e32 v178, v182
	v_mov_b32_e32 v179, v183
	s_cbranch_scc1 .LBB0_2138
	s_add_i32 s40, s70, s90
	s_ashr_i32 s41, s40, 31
	s_lshl_b64 s[42:43], s[40:41], 7
	s_lshl_b64 s[44:45], s[40:41], 9
	s_add_u32 s44, s51, s44
	s_addc_u32 s45, s55, s45
	s_add_u32 s42, s66, s42
	s_addc_u32 s43, s67, s43
	s_lshl_b32 s40, s40, 1
	s_ashr_i32 s41, s40, 31
	s_lshl_b64 s[40:41], s[40:41], 2
	v_lshl_add_u64 v[92:93], v[96:97], 2, s[44:45]
	v_lshl_add_u64 v[94:95], s[42:43], 0, v[96:97]
	s_add_u32 s40, s61, s40
	global_load_dwordx4 v[72:75], v[92:93], off offset:32
	global_load_dwordx4 v[76:79], v[92:93], off offset:16
	global_load_dwordx4 v[88:91], v[92:93], off offset:48
	global_load_dwordx4 v[160:163], v[94:95], off
	s_addc_u32 s41, s68, s41
	global_load_dwordx4 v[92:95], v[92:93], off
	s_nop 0
	global_load_dwordx2 v[178:179], v98, s[40:41]

; template <bool VPASS>
; __device__ __forceinline__ void peer_pass(Frame& F, int c, int rank, int nblk) {
;     ...
;             vb = vm;
;         }
;         va = vn;
;     }
.LBB0_2141:
	s_add_i32 s76, s76, 2
	s_add_i32 s74, s74, s73
	s_add_i32 s70, s70, s69
	v_mov_b64_e32 v[170:171], v[166:167]
	s_waitcnt vmcnt(1)
	v_mov_b64_e32 v[160:161], v[172:173]
	s_cmp_lt_i32 s77, s50
	v_mov_b32_e32 v183, v181
	v_mov_b32_e32 v182, v180
	v_mov_b64_e32 v[168:169], v[164:165]
	s_waitcnt vmcnt(1)
	v_mov_b32_e32 v179, v185
	v_mov_b32_e32 v178, v184
	v_mov_b64_e32 v[162:163], v[174:175]
	s_cbranch_scc0 .LBB0_2156

; __device__ __forceinline__ void v_compute(const u32x4 (&w)[16], const PeerVisit& v, bf16* po, int lane) {
;     i32x4v a1[4], a2[4];
; #pragma unroll
;     for (int q = 0; q < 4; ++q) { a1[q] = (i32x4v){0, 0, 0, 0}; a2[q] = (i32x4v){0, 0, 0, 0}; }
;     const unsigned cq[4] = {v.x.x, v.x.y, v.x.z, v.x.w};
;     unsigned selq[4];
; #pragma unroll
;     for (int sI = 0; sI < 4; ++sI) selq[sI] = 0x0C0C0C0Cu ^ ((0x0Cu ^ (unsigned)sI) << (8 * (lane & 3)));
; #pragma unroll
;     for (int it = 0; it < 16; ++it) {
;         const int A = (int)__builtin_amdgcn_perm(0u, cq[it >> 2], selq[it & 3]);
; #pragma unroll
;         for (int q = 0; q < 4; ++q) {
;             a1[q] = __builtin_amdgcn_mfma_i32_4x4x4i8(A, (int)w[it][q], a1[q], 0, 0, 0);
;             a2[q] = __builtin_amdgcn_mfma_i32_4x4x4i8(A, (int)(w[it][q] & 0xF0F0F0F0u), a2[q], 0, 0, 0);
;         }
;     }
.LBB0_2146:
	v_lshlrev_b32_e32 v176, 3, v186
	v_lshlrev_b32_e64 v172, v176, 12
	v_xor_b32_e32 v189, 0xc0c0c0c, v172
	v_perm_b32 v184, 0, v168, v189
	v_and_b32_e32 v185, 0xf0f0f0f0, v16
	v_and_b32_e32 v187, 0xf0f0f0f0, v18
	v_and_b32_e32 v191, 0xf0f0f0f0, v66
	v_and_b32_e32 v224, 0xf0f0f0f0, v82
	v_mfma_i32_4x4x4_16b_i8 v[192:195], v184, v185, 0
	v_and_b32_e32 v185, 0xf0f0f0f0, v17
	v_mfma_i32_4x4x4_16b_i8 v[172:175], v184, v16, 0
	v_and_b32_e32 v220, 0xf0f0f0f0, v67
	v_mfma_i32_4x4x4_16b_i8 v[200:203], v184, v185, 0
	v_lshlrev_b32_e64 v185, v176, 13
	v_xor_b32_e32 v190, 0xc0c0c0c, v185
	v_and_b32_e32 v185, 0xf0f0f0f0, v19
	v_mfma_i32_4x4x4_16b_i8 v[196:199], v184, v17, 0
	v_perm_b32 v221, 0, v171, v190
	v_mfma_i32_4x4x4_16b_i8 v[204:207], v184, v18, 0
	v_and_b32_e32 v227, 0xf0f0f0f0, v84
	v_mfma_i32_4x4x4_16b_i8 v[208:211], v184, v187, 0
	v_and_b32_e32 v187, 0xf0f0f0f0, v22
	v_mfma_i32_4x4x4_16b_i8 v[212:215], v184, v19, 0
	v_and_b32_e32 v222, 0xf0f0f0f0, v69
	v_mfma_i32_4x4x4_16b_i8 v[216:219], v184, v185, 0
	v_perm_b32 v184, 0, v168, v190
	v_and_b32_e32 v185, 0xf0f0f0f0, v20
	v_and_b32_e32 v223, 0xf0f0f0f0, v81
	v_mfma_i32_4x4x4_16b_i8 v[172:175], v184, v20, v[172:175]
	v_and_b32_e32 v225, 0xf0f0f0f0, v83
	v_mfma_i32_4x4x4_16b_i8 v[192:195], v184, v185, v[192:195]
	v_and_b32_e32 v185, 0xf0f0f0f0, v21
	v_mfma_i32_4x4x4_16b_i8 v[196:199], v184, v21, v[196:199]
	v_and_b32_e32 v228, 0xf0f0f0f0, v85
	v_mfma_i32_4x4x4_16b_i8 v[200:203], v184, v185, v[200:203]
	v_lshlrev_b32_e64 v185, v176, 14
	v_xor_b32_e32 v188, 0xc0c0c0c, v185
	v_and_b32_e32 v185, 0xf0f0f0f0, v23
	v_mfma_i32_4x4x4_16b_i8 v[204:207], v184, v22, v[204:207]
	v_lshlrev_b32_e64 v176, v176, 15
	v_mfma_i32_4x4x4_16b_i8 v[208:211], v184, v187, v[208:211]
	v_xor_b32_e32 v187, 0xc0c0c0c, v176
	v_mfma_i32_4x4x4_16b_i8 v[212:215], v184, v23, v[212:215]
	v_and_b32_e32 v176, 0xf0f0f0f0, v27
	v_mfma_i32_4x4x4_16b_i8 v[216:219], v184, v185, v[216:219]
	v_perm_b32 v184, 0, v168, v188
	v_perm_b32 v168, 0, v168, v187
	v_and_b32_e32 v185, 0xf0f0f0f0, v24
	v_mfma_i32_4x4x4_16b_i8 v[216:219], v184, v176, v[216:219]
	v_and_b32_e32 v176, 0xf0f0f0f0, v28
	v_mfma_i32_4x4x4_16b_i8 v[192:195], v184, v185, v[192:195]
	v_and_b32_e32 v185, 0xf0f0f0f0, v25
	v_mfma_i32_4x4x4_16b_i8 v[172:175], v184, v24, v[172:175]
	v_perm_b32 v226, 0, v171, v187
	v_mfma_i32_4x4x4_16b_i8 v[200:203], v184, v185, v[200:203]
	v_and_b32_e32 v185, 0xf0f0f0f0, v26
	v_mfma_i32_4x4x4_16b_i8 v[192:195], v168, v176, v[192:195]
	v_and_b32_e32 v176, 0xf0f0f0f0, v29
	v_mfma_i32_4x4x4_16b_i8 v[208:211], v184, v185, v[208:211]
	v_and_b32_e32 v185, 0xf0f0f0f0, v64
	v_mfma_i32_4x4x4_16b_i8 v[196:199], v184, v25, v[196:199]
	v_mfma_i32_4x4x4_16b_i8 v[204:207], v184, v26, v[204:207]
	v_mfma_i32_4x4x4_16b_i8 v[212:215], v184, v27, v[212:215]
	v_and_b32_e32 v184, 0xf0f0f0f0, v61
	v_mfma_i32_4x4x4_16b_i8 v[200:203], v168, v176, v[200:203]
	v_and_b32_e32 v176, 0xf0f0f0f0, v30
	v_mfma_i32_4x4x4_16b_i8 v[172:175], v168, v28, v[172:175]
	s_nop 0
	v_mfma_i32_4x4x4_16b_i8 v[208:211], v168, v176, v[208:211]
	v_and_b32_e32 v176, 0xf0f0f0f0, v31
	v_mfma_i32_4x4x4_16b_i8 v[196:199], v168, v29, v[196:199]
	v_mfma_i32_4x4x4_16b_i8 v[204:207], v168, v30, v[204:207]
	v_mfma_i32_4x4x4_16b_i8 v[212:215], v168, v31, v[212:215]
	v_mfma_i32_4x4x4_16b_i8 v[216:219], v168, v176, v[216:219]
	v_perm_b32 v168, 0, v169, v189
	v_and_b32_e32 v176, 0xf0f0f0f0, v32
	s_nop 0
	v_mfma_i32_4x4x4_16b_i8 v[172:175], v168, v32, v[172:175]
	v_mfma_i32_4x4x4_16b_i8 v[192:195], v168, v176, v[192:195]
	v_and_b32_e32 v176, 0xf0f0f0f0, v33
	v_mfma_i32_4x4x4_16b_i8 v[196:199], v168, v33, v[196:199]
	s_nop 0
	v_mfma_i32_4x4x4_16b_i8 v[200:203], v168, v176, v[200:203]
	v_and_b32_e32 v176, 0xf0f0f0f0, v34
	v_mfma_i32_4x4x4_16b_i8 v[204:207], v168, v34, v[204:207]
	s_nop 0
	v_mfma_i32_4x4x4_16b_i8 v[208:211], v168, v176, v[208:211]
	v_and_b32_e32 v176, 0xf0f0f0f0, v35
	v_mfma_i32_4x4x4_16b_i8 v[212:215], v168, v35, v[212:215]
	s_nop 0
	v_mfma_i32_4x4x4_16b_i8 v[216:219], v168, v176, v[216:219]
	v_perm_b32 v168, 0, v169, v190
	v_and_b32_e32 v176, 0xf0f0f0f0, v36
	s_nop 0
	v_mfma_i32_4x4x4_16b_i8 v[172:175], v168, v36, v[172:175]
	v_mfma_i32_4x4x4_16b_i8 v[192:195], v168, v176, v[192:195]
	v_and_b32_e32 v176, 0xf0f0f0f0, v37
	v_mfma_i32_4x4x4_16b_i8 v[196:199], v168, v37, v[196:199]
	s_nop 0
	v_mfma_i32_4x4x4_16b_i8 v[200:203], v168, v176, v[200:203]
	v_and_b32_e32 v176, 0xf0f0f0f0, v38
	v_mfma_i32_4x4x4_16b_i8 v[204:207], v168, v38, v[204:207]
	s_nop 0
	v_mfma_i32_4x4x4_16b_i8 v[208:211], v168, v176, v[208:211]
	v_and_b32_e32 v176, 0xf0f0f0f0, v39
	v_mfma_i32_4x4x4_16b_i8 v[212:215], v168, v39, v[212:215]
	s_nop 0
	v_mfma_i32_4x4x4_16b_i8 v[216:219], v168, v176, v[216:219]
	v_perm_b32 v168, 0, v169, v188
	v_and_b32_e32 v176, 0xf0f0f0f0, v40
	s_nop 0
	v_mfma_i32_4x4x4_16b_i8 v[172:175], v168, v40, v[172:175]
	v_mfma_i32_4x4x4_16b_i8 v[192:195], v168, v176, v[192:195]
	v_and_b32_e32 v176, 0xf0f0f0f0, v41
	v_mfma_i32_4x4x4_16b_i8 v[196:199], v168, v41, v[196:199]
	s_nop 0
	v_mfma_i32_4x4x4_16b_i8 v[200:203], v168, v176, v[200:203]
	v_and_b32_e32 v176, 0xf0f0f0f0, v42
	v_mfma_i32_4x4x4_16b_i8 v[204:207], v168, v42, v[204:207]
	s_nop 0
	v_mfma_i32_4x4x4_16b_i8 v[208:211], v168, v176, v[208:211]
	v_and_b32_e32 v176, 0xf0f0f0f0, v43
	v_mfma_i32_4x4x4_16b_i8 v[212:215], v168, v43, v[212:215]
	s_nop 0
	v_mfma_i32_4x4x4_16b_i8 v[216:219], v168, v176, v[216:219]
	v_perm_b32 v168, 0, v169, v187
	v_and_b32_e32 v169, 0xf0f0f0f0, v44
	v_and_b32_e32 v176, 0xf0f0f0f0, v58
	v_mfma_i32_4x4x4_16b_i8 v[172:175], v168, v44, v[172:175]
	v_mfma_i32_4x4x4_16b_i8 v[192:195], v168, v169, v[192:195]
; __device__ __forceinline__ void v_compute(const u32x4 (&w)[16], const PeerVisit& v, bf16* po, int lane) {
;     ...
;     for (int it = 0; it < 16; ++it) {
;         const int A = (int)__builtin_amdgcn_perm(0u, cq[it >> 2], selq[it & 3]);
; #pragma unroll
;         for (int q = 0; q < 4; ++q) {
;             a1[q] = __builtin_amdgcn_mfma_i32_4x4x4i8(A, (int)w[it][q], a1[q], 0, 0, 0);
;             a2[q] = __builtin_amdgcn_mfma_i32_4x4x4i8(A, (int)(w[it][q] & 0xF0F0F0F0u), a2[q], 0, 0, 0);
;         }
;     }
;     int r1[2][4], r2[2][4];
; #pragma unroll
;     for (int jj = 0; jj < 2; ++jj)
; #pragma unroll
;         for (int i = 0; i < 4; ++i) {
;             const auto t1 = __builtin_amdgcn_permlane32_swap((unsigned)a1[jj][i], (unsigned)a1[jj + 2][i], false, false); r1[jj][i] = (int)t1[0] + (int)t1[1];
;             const auto t2 = __builtin_amdgcn_permlane32_swap((unsigned)a2[jj][i], (unsigned)a2[jj + 2][i], false, false); r2[jj][i] = (int)t2[0] + (int)t2[1];
;         }
	v_and_b32_e32 v169, 0xf0f0f0f0, v45
	v_mfma_i32_4x4x4_16b_i8 v[196:199], v168, v45, v[196:199]
	s_nop 0
	v_mfma_i32_4x4x4_16b_i8 v[200:203], v168, v169, v[200:203]
	v_and_b32_e32 v169, 0xf0f0f0f0, v46
	v_mfma_i32_4x4x4_16b_i8 v[204:207], v168, v46, v[204:207]
	s_nop 0
	v_mfma_i32_4x4x4_16b_i8 v[208:211], v168, v169, v[208:211]
	v_and_b32_e32 v169, 0xf0f0f0f0, v47
	v_mfma_i32_4x4x4_16b_i8 v[212:215], v168, v47, v[212:215]
	s_nop 0
	v_mfma_i32_4x4x4_16b_i8 v[216:219], v168, v169, v[216:219]
	v_perm_b32 v168, 0, v170, v189
	v_and_b32_e32 v169, 0xf0f0f0f0, v48
	s_nop 0
	v_mfma_i32_4x4x4_16b_i8 v[172:175], v168, v48, v[172:175]
	v_mfma_i32_4x4x4_16b_i8 v[192:195], v168, v169, v[192:195]
	v_and_b32_e32 v169, 0xf0f0f0f0, v49
	v_mfma_i32_4x4x4_16b_i8 v[196:199], v168, v49, v[196:199]
	s_nop 0
	v_mfma_i32_4x4x4_16b_i8 v[200:203], v168, v169, v[200:203]
	v_and_b32_e32 v169, 0xf0f0f0f0, v50
	v_mfma_i32_4x4x4_16b_i8 v[204:207], v168, v50, v[204:207]
	s_nop 0
	v_mfma_i32_4x4x4_16b_i8 v[208:211], v168, v169, v[208:211]
	v_and_b32_e32 v169, 0xf0f0f0f0, v51
	v_mfma_i32_4x4x4_16b_i8 v[212:215], v168, v51, v[212:215]
	s_nop 0
	v_mfma_i32_4x4x4_16b_i8 v[216:219], v168, v169, v[216:219]
	v_perm_b32 v168, 0, v170, v190
	v_and_b32_e32 v169, 0xf0f0f0f0, v52
	s_nop 0
	v_mfma_i32_4x4x4_16b_i8 v[172:175], v168, v52, v[172:175]
	v_mfma_i32_4x4x4_16b_i8 v[192:195], v168, v169, v[192:195]
	v_and_b32_e32 v169, 0xf0f0f0f0, v53
	v_mfma_i32_4x4x4_16b_i8 v[196:199], v168, v53, v[196:199]
	s_nop 0
	v_mfma_i32_4x4x4_16b_i8 v[200:203], v168, v169, v[200:203]
	v_and_b32_e32 v169, 0xf0f0f0f0, v54
	v_mfma_i32_4x4x4_16b_i8 v[204:207], v168, v54, v[204:207]
	s_nop 0
	v_mfma_i32_4x4x4_16b_i8 v[208:211], v168, v169, v[208:211]
	v_and_b32_e32 v169, 0xf0f0f0f0, v55
	v_mfma_i32_4x4x4_16b_i8 v[212:215], v168, v55, v[212:215]
	s_nop 0
	v_mfma_i32_4x4x4_16b_i8 v[216:219], v168, v169, v[216:219]
	v_perm_b32 v168, 0, v170, v188
	v_perm_b32 v170, 0, v170, v187
	v_and_b32_e32 v169, 0xf0f0f0f0, v56
	v_mfma_i32_4x4x4_16b_i8 v[208:211], v168, v176, v[208:211]
	v_and_b32_e32 v176, 0xf0f0f0f0, v60
	v_mfma_i32_4x4x4_16b_i8 v[192:195], v168, v169, v[192:195]
	v_and_b32_e32 v169, 0xf0f0f0f0, v57
	v_mfma_i32_4x4x4_16b_i8 v[172:175], v168, v56, v[172:175]
	v_mfma_i32_4x4x4_16b_i8 v[192:195], v170, v176, v[192:195]
	v_perm_b32 v176, 0, v171, v189
	v_mfma_i32_4x4x4_16b_i8 v[200:203], v168, v169, v[200:203]
	v_and_b32_e32 v169, 0xf0f0f0f0, v59
	v_mfma_i32_4x4x4_16b_i8 v[196:199], v168, v57, v[196:199]
	v_mfma_i32_4x4x4_16b_i8 v[204:207], v168, v58, v[204:207]
	v_mfma_i32_4x4x4_16b_i8 v[212:215], v168, v59, v[212:215]
	v_mfma_i32_4x4x4_16b_i8 v[216:219], v168, v169, v[216:219]
	v_and_b32_e32 v168, 0xf0f0f0f0, v62
	v_mfma_i32_4x4x4_16b_i8 v[204:207], v170, v62, v[204:207]
	v_and_b32_e32 v169, 0xf0f0f0f0, v63
	v_mfma_i32_4x4x4_16b_i8 v[208:211], v170, v168, v[208:211]
	v_and_b32_e32 v168, 0xf0f0f0f0, v68
	v_mfma_i32_4x4x4_16b_i8 v[172:175], v170, v60, v[172:175]
	v_mfma_i32_4x4x4_16b_i8 v[208:211], v176, v191, v[208:211]
	v_perm_b32 v191, 0, v171, v188
	v_mfma_i32_4x4x4_16b_i8 v[192:195], v176, v185, v[192:195]
	v_and_b32_e32 v185, 0xf0f0f0f0, v71
	v_mfma_i32_4x4x4_16b_i8 v[204:207], v176, v66, v[204:207]
	v_mfma_i32_4x4x4_16b_i8 v[216:219], v170, v169, v[216:219]
	v_and_b32_e32 v169, 0xf0f0f0f0, v70
	v_mfma_i32_4x4x4_16b_i8 v[172:175], v176, v64, v[172:175]
	v_mfma_i32_4x4x4_16b_i8 v[192:195], v221, v168, v[192:195]
	v_mfma_i32_4x4x4_16b_i8 v[204:207], v221, v70, v[204:207]
	v_mfma_i32_4x4x4_16b_i8 v[208:211], v221, v169, v[208:211]
	v_mfma_i32_4x4x4_16b_i8 v[196:199], v170, v61, v[196:199]
	v_mfma_i32_4x4x4_16b_i8 v[200:203], v170, v184, v[200:203]
	v_and_b32_e32 v184, 0xf0f0f0f0, v65
	v_mfma_i32_4x4x4_16b_i8 v[212:215], v170, v63, v[212:215]
	v_and_b32_e32 v170, 0xf0f0f0f0, v80
	v_mfma_i32_4x4x4_16b_i8 v[172:175], v221, v68, v[172:175]
	s_nop 0
	v_mfma_i32_4x4x4_16b_i8 v[168:171], v191, v170, v[192:195]
	v_mfma_i32_4x4x4_16b_i8 v[192:195], v191, v82, v[204:207]
	v_mfma_i32_4x4x4_16b_i8 v[204:207], v191, v224, v[208:211]
	v_and_b32_e32 v224, 0xf0f0f0f0, v87
	v_mfma_i32_4x4x4_16b_i8 v[172:175], v191, v80, v[172:175]
	v_and_b32_e32 v208, 0xf0f0f0f0, v86
	v_mfma_i32_4x4x4_16b_i8 v[196:199], v176, v65, v[196:199]
	s_nop 0
	v_mfma_i32_4x4x4_16b_i8 v[204:207], v226, v208, v[204:207]
	v_mfma_i32_4x4x4_16b_i8 v[200:203], v176, v184, v[200:203]
	v_mfma_i32_4x4x4_16b_i8 v[208:211], v176, v67, v[212:215]
	v_mfma_i32_4x4x4_16b_i8 v[212:215], v176, v220, v[216:219]
	v_mfma_i32_4x4x4_16b_i8 v[172:175], v226, v84, v[172:175]
	v_mfma_i32_4x4x4_16b_i8 v[192:195], v226, v86, v[192:195]
	v_mfma_i32_4x4x4_16b_i8 v[168:171], v226, v227, v[168:171]
	v_mfma_i32_4x4x4_16b_i8 v[196:199], v221, v69, v[196:199]
	v_mfma_i32_4x4x4_16b_i8 v[200:203], v221, v222, v[200:203]
	s_nop 1
	v_permlane32_swap_b32_e32 v172, v192
	v_mfma_i32_4x4x4_16b_i8 v[208:211], v221, v71, v[208:211]
	v_permlane32_swap_b32_e32 v173, v193
	v_mfma_i32_4x4x4_16b_i8 v[212:215], v221, v185, v[212:215]
	v_permlane32_swap_b32_e32 v169, v205
	v_permlane32_swap_b32_e32 v174, v194
	v_permlane32_swap_b32_e32 v170, v206
	v_permlane32_swap_b32_e32 v175, v195
	v_add_u32_e32 v227, v172, v192
	v_add_u32_e32 v184, v173, v193
	v_add_u32_e32 v176, v169, v205
	v_add_u32_e32 v205, v174, v194
	v_mfma_i32_4x4x4_16b_i8 v[196:199], v191, v81, v[196:199]
	v_add_u32_e32 v185, v170, v206
	v_mfma_i32_4x4x4_16b_i8 v[200:203], v191, v223, v[200:203]
	v_add_u32_e32 v206, v175, v195
	v_mfma_i32_4x4x4_16b_i8 v[208:211], v191, v83, v[208:211]
	v_permlane32_swap_b32_e32 v168, v204
	v_mfma_i32_4x4x4_16b_i8 v[172:175], v191, v225, v[212:215]
	v_permlane32_swap_b32_e32 v171, v207
; __device__ __forceinline__ unsigned cvt_pk_bf16(float lo, float hi) { unsigned r; asm volatile("v_cvt_pk_bf16_f32 %0, %1, %2" : "=v"(r) : "v"(lo), "v"(hi)); return r; }
; __device__ __forceinline__ void v_compute(const u32x4 (&w)[16], const PeerVisit& v, bf16* po, int lane) {
;     ...
;     int s1[4], s2[4];
; #pragma unroll
;     for (int i = 0; i < 4; ++i) {
;         const auto t1 = __builtin_amdgcn_permlane16_swap((unsigned)r1[0][i], (unsigned)r1[1][i], false, false); s1[i] = (int)t1[0] + (int)t1[1];
;         const auto t2 = __builtin_amdgcn_permlane16_swap((unsigned)r2[0][i], (unsigned)r2[1][i], false, false); s2[i] = (int)t2[0] + (int)t2[1];
;         s1[i] += __builtin_amdgcn_update_dpp(0, s1[i], 0x128, 0xF, 0xF, false);
;         s2[i] += __builtin_amdgcn_update_dpp(0, s2[i], 0x128, 0xF, 0xF, false);
;     }
;     if (!(lane & 8)) {
;         const float csf = (float)v.cs; float lo[4], hi[4];
; #pragma unroll
;         for (int i = 0; i < 4; ++i) { lo[i] = ((float)(s1[i] - s2[i]) - 7.5f * csf) * v.sc; hi[i] = ((float)s2[i] * 0.0625f + 0.5f * csf) * v.sc; }
;         u32x4 o;
;         o.x = cvt_pk_bf16(lo[0], lo[1]); o.y = cvt_pk_bf16(lo[2], lo[3]); o.z = cvt_pk_bf16(hi[0], hi[1]); o.w = cvt_pk_bf16(hi[2], hi[3]);
;         __builtin_nontemporal_store(o, (u32x4*)(po + (lane & 7) * 32 + 8 * (((lane >> 4) & 1) + 2 * (lane >> 5))));
;     }
; template <bool VPASS>
; __device__ __forceinline__ void peer_pass(Frame& F, int c, int rank, int nblk) {
;     ...
;         if (v + 1 < nvis) rows16_load(wb, T, vb, lane);
;         if (v + 2 < nvis) vn = visit_load<VPASS>(F.ws, FQc, tok + 2 * step, lane);
;         if (VPASS) v_compute(wa, va, PO + (size_t)tok * D, lane); else u_compute(wa, va, PD + (size_t)tok * 128, lane);
;         if (v + 1 < nvis) {
;             PeerVisit vm = vb;
;             if (v + 2 < nvis) rows16_load(wa, T, vn, lane);
;             if (v + 3 < nvis) vm = visit_load<VPASS>(F.ws, FQc, tok + 3 * step, lane);
	v_add_u32_e32 v204, v168, v204
	v_mfma_i32_4x4x4_16b_i8 v[192:195], v226, v85, v[196:199]
	v_add_u32_e32 v207, v171, v207
	v_mfma_i32_4x4x4_16b_i8 v[168:171], v226, v87, v[208:211]
	v_mfma_i32_4x4x4_16b_i8 v[196:199], v226, v228, v[200:203]
	v_mfma_i32_4x4x4_16b_i8 v[172:175], v226, v224, v[172:175]
	s_nop 2
	v_permlane32_swap_b32_e32 v192, v168
	v_permlane32_swap_b32_e32 v193, v169
	v_permlane32_swap_b32_e32 v196, v172
	v_permlane32_swap_b32_e32 v197, v173
	v_permlane32_swap_b32_e32 v194, v170
	v_permlane32_swap_b32_e32 v198, v174
	v_permlane32_swap_b32_e32 v195, v171
	v_permlane32_swap_b32_e32 v199, v175
	v_add_u32_e32 v168, v192, v168
	v_add_u32_e32 v172, v196, v172
	v_add_u32_e32 v191, v193, v169
	v_add_u32_e32 v173, v197, v173
	v_add_u32_e32 v192, v194, v170
	v_add_u32_e32 v193, v198, v174
	v_add_u32_e32 v194, v195, v171
	v_add_u32_e32 v195, v199, v175
	v_permlane16_swap_b32_e32 v227, v168
	v_permlane16_swap_b32_e32 v204, v172
	v_permlane16_swap_b32_e32 v184, v191
	v_permlane16_swap_b32_e32 v176, v173
	v_permlane16_swap_b32_e32 v205, v192
	v_permlane16_swap_b32_e32 v185, v193
	v_permlane16_swap_b32_e32 v206, v194
	v_permlane16_swap_b32_e32 v207, v195
	v_add_u32_e32 v168, v227, v168
	v_add_u32_e32 v169, v204, v172
	v_mov_b32_e32 v170, 0
	v_mov_b32_e32 v171, 0
	v_add_u32_e32 v172, v184, v191
	v_add_u32_e32 v173, v176, v173
	v_mov_b32_e32 v174, 0
	v_mov_b32_e32 v175, 0
	v_add_u32_e32 v176, v205, v192
	v_add_u32_e32 v184, v185, v193
	v_mov_b32_e32 v185, 0
	v_mov_b32_e32 v191, 0
	v_add_u32_e32 v192, v206, v194
	v_add_u32_e32 v193, v207, v195
	v_mov_b32_e32 v194, 0
	v_mov_b32_e32 v195, 0
	v_and_b32_e32 v196, 8, v186
	v_mov_b32_dpp v170, v168 row_ror:8 row_mask:0xf bank_mask:0xf
	v_mov_b32_dpp v171, v169 row_ror:8 row_mask:0xf bank_mask:0xf
	v_mov_b32_dpp v174, v172 row_ror:8 row_mask:0xf bank_mask:0xf
	v_mov_b32_dpp v175, v173 row_ror:8 row_mask:0xf bank_mask:0xf
	v_mov_b32_dpp v185, v176 row_ror:8 row_mask:0xf bank_mask:0xf
	v_mov_b32_dpp v191, v184 row_ror:8 row_mask:0xf bank_mask:0xf
	v_mov_b32_dpp v194, v192 row_ror:8 row_mask:0xf bank_mask:0xf
	v_mov_b32_dpp v195, v193 row_ror:8 row_mask:0xf bank_mask:0xf
	v_cmp_eq_u32_e64 s[40:41], 0, v196
	s_and_saveexec_b64 s[48:49], s[40:41]
	s_cbranch_execz .LBB0_2148
	v_add_u32_e32 v169, v171, v169
	v_add_u32_e32 v168, v170, v168
	v_add_u32_e32 v173, v175, v173
	v_add_u32_e32 v172, v174, v172
	v_sub_u32_e32 v168, v168, v169
	v_cvt_f32_i32_e32 v170, v168
	v_sub_u32_e32 v168, v172, v173
	v_add_u32_e32 v184, v191, v184
	v_add_u32_e32 v176, v185, v176
	v_cvt_f32_i32_e32 v172, v168
	v_cvt_f32_i32_e32 v168, v183
	v_cvt_f32_i32_e32 v174, v169
	v_sub_u32_e32 v171, v176, v184
	v_cvt_f32_i32_e32 v169, v184
	v_cvt_f32_i32_e32 v175, v171
	v_cvt_f32_i32_e32 v173, v173
	v_fmac_f32_e32 v170, 0xc0f00000, v168
	v_mul_f32_e32 v176, v182, v170
	v_pk_mul_f32 v[170:171], v[168:169], s[42:43]
	v_add_u32_e32 v193, v195, v193
	v_add_u32_e32 v192, v194, v192
	v_fmamk_f32 v169, v174, 0x3d800000, v170
	v_fmac_f32_e32 v172, 0xc0f00000, v168
	v_fmac_f32_e32 v175, 0xc0f00000, v168
	v_mul_f32_e32 v174, v182, v169
	v_mul_f32_e32 v169, v182, v172
	v_fmamk_f32 v172, v173, 0x3d800000, v170
	v_mul_f32_e32 v173, v182, v175
	v_sub_u32_e32 v175, v192, v193
	v_cvt_f32_i32_e32 v175, v175
	v_cvt_f32_i32_e32 v183, v193
	s_ashr_i32 s71, s70, 31
	v_add_f32_e32 v171, v170, v171
	v_fmac_f32_e32 v175, 0xc0f00000, v168
	v_mul_f32_e32 v175, v182, v175
	v_fmac_f32_e32 v170, 0x3d800000, v183
	v_cvt_pk_bf16_f32 v168, v176, v169
	v_cvt_pk_bf16_f32 v169, v173, v175
	v_ashrrev_i32_e32 v175, 4, v186
	s_lshl_b64 s[78:79], s[70:71], 12
	v_mul_f32_e32 v172, v182, v172
	v_mul_f32_e32 v171, v182, v171
	v_mul_f32_e32 v182, v182, v170
	v_cvt_pk_bf16_f32 v170, v174, v172
	v_lshrrev_b32_e32 v174, 4, v186
	v_and_b32_e32 v175, 0x1ffffffe, v175
	s_add_u32 s78, s62, s78
	v_lshlrev_b32_e32 v172, 6, v186
	v_and_or_b32 v174, v174, 1, v175
	s_addc_u32 s79, s63, s79
	v_and_b32_e32 v176, 0x1c0, v172
	v_lshlrev_b32_e32 v174, 3, v174
	v_lshl_add_u64 v[172:173], s[78:79], 0, v[176:177]
	v_ashrrev_i32_e32 v175, 31, v174
	v_lshl_add_u64 v[172:173], v[174:175], 1, v[172:173]
	v_cvt_pk_bf16_f32 v171, v171, v182
	global_store_dwordx4 v[172:173], v[168:171], off nt
.LBB0_2148:
	s_or_b64 exec, exec, s[48:49]
	s_waitcnt vmcnt(1)
	s_andn2_b64 vcc, exec, s[44:45]
	s_cbranch_vccnz .LBB0_2155
	s_andn2_b64 vcc, exec, s[46:47]
	s_cbranch_vccnz .LBB0_2151
	v_lshlrev_b32_e32 v16, 4, v186
	v_and_b32_e32 v80, 0x70, v16
	v_lshl_or_b32 v16, v12, 7, v80
	v_lshl_or_b32 v20, v13, 7, v80
	v_lshl_or_b32 v24, v14, 7, v80
	v_lshl_or_b32 v28, v15, 7, v80
	v_lshl_or_b32 v32, v8, 7, v80
	v_lshl_or_b32 v36, v9, 7, v80
	v_lshl_or_b32 v40, v10, 7, v80
	v_lshl_or_b32 v44, v11, 7, v80
	v_lshl_or_b32 v48, v4, 7, v80
	v_lshl_or_b32 v52, v5, 7, v80
	v_lshl_or_b32 v56, v6, 7, v80
	v_lshl_or_b32 v60, v7, 7, v80
	v_lshl_or_b32 v64, v0, 7, v80
	v_lshl_or_b32 v68, v1, 7, v80
	v_lshl_or_b32 v81, v2, 7, v80
	v_lshl_or_b32 v84, v3, 7, v80
	global_load_dwordx4 v[16:19], v16, s[2:3]
	s_nop 0
	global_load_dwordx4 v[20:23], v20, s[2:3]
	s_nop 0
	global_load_dwordx4 v[24:27], v24, s[2:3]
	s_nop 0
	global_load_dwordx4 v[28:31], v28, s[2:3]
	s_nop 0
	global_load_dwordx4 v[32:35], v32, s[2:3]
	s_nop 0
	global_load_dwordx4 v[36:39], v36, s[2:3]
	s_nop 0
	global_load_dwordx4 v[40:43], v40, s[2:3]
	s_nop 0
	global_load_dwordx4 v[44:47], v44, s[2:3]
	s_nop 0
	global_load_dwordx4 v[48:51], v48, s[2:3]
	s_nop 0
	global_load_dwordx4 v[52:55], v52, s[2:3]
	s_nop 0
	global_load_dwordx4 v[56:59], v56, s[2:3]
	s_nop 0
	global_load_dwordx4 v[60:63], v60, s[2:3]
	s_nop 0
	global_load_dwordx4 v[64:67], v64, s[2:3]
	s_nop 0
	global_load_dwordx4 v[68:71], v68, s[2:3]
	s_nop 0
	global_load_dwordx4 v[80:83], v81, s[2:3]
	s_nop 0
	global_load_dwordx4 v[84:87], v84, s[2:3]
